# SSD pass1 entry: the remaining tile-prefetch loads are issued before the wait for the a_log pair (vmcnt 8 instead of 3)
# speedup vs baseline: 1.0086x; 1.0030x over previous
.LBB0_411:
	s_andn2_b64 vcc, exec, s[14:15]
	s_cbranch_vccnz .LBB0_14
	s_cmp_lt_i32 s3, 2
	s_mov_b64 s[14:15], -1
	s_cbranch_scc1 .LBB0_558
	s_cmp_lt_i32 s3, 3
	s_cbranch_scc1 .LBB0_490
	s_cmp_eq_u32 s3, 3
	s_cbranch_scc0 .LBB0_489
	v_readlane_b32 s16, v253, 24
	v_readlane_b32 s17, v253, 25
	s_and_b64 vcc, exec, s[16:17]
	v_readlane_b32 s35, v253, 40
	v_readlane_b32 s24, v253, 32
	s_cbranch_vccz .LBB0_429
	s_waitcnt lgkmcnt(0)
	s_add_u32 s14, s4, 0xe00000
	s_waitcnt vmcnt(0)
	v_add_u32_e32 v8, 0x200, v234
	s_addc_u32 s15, s5, 0
	v_and_b32_e32 v1, 15, v234
	s_waitcnt vmcnt(0)
	v_ashrrev_i32_e32 v38, 4, v234
	v_readlane_b32 s18, v253, 34
	v_ashrrev_i32_e32 v39, 4, v8
	v_lshlrev_b32_e32 v14, 3, v1
	v_readlane_b32 s16, v253, 33
	v_add_u32_e32 v4, s18, v38
	v_mov_b64_e32 v[24:25], s[14:15]
	v_add_u32_e32 v8, s18, v39
	v_or_b32_e32 v2, s16, v14
	v_mad_i64_i32 v[12:13], s[16:17], v4, s95, v[24:25]
	v_mad_i64_i32 v[16:17], s[16:17], v8, s95, v[24:25]
	v_readlane_b32 s16, v253, 26
	v_lshlrev_b32_e32 v2, 1, v2
	v_mov_b32_e32 v77, v3
	v_add_u32_e32 v14, s16, v14
	v_lshlrev_b32_e32 v76, 1, v14
	v_lshl_add_u64 v[8:9], v[16:17], 0, v[2:3]
	v_lshl_add_u64 v[16:17], v[16:17], 0, v[76:77]
	v_readlane_b32 s19, v253, 35
	global_load_dwordx4 v[20:23], v[16:17], off offset:2048
	s_lshl_b32 s36, s48, 4
	v_add_u32_e32 v16, s19, v38
	v_add_u32_e32 v26, s19, v39
	v_mad_i64_i32 v[28:29], s[16:17], v16, s95, v[24:25]
	v_mad_i64_i32 v[32:33], s[16:17], v26, s95, v[24:25]
	s_and_b32 s16, s49, 0xffffffc0
	s_nop 0
	v_or_b32_e32 v40, s16, v204
	v_add_u32_e32 v36, s18, v40
	v_ashrrev_i32_e32 v37, 31, v36
	v_lshlrev_b64 v[36:37], 6, v[36:37]
	v_readlane_b32 s18, v253, 27
	v_lshl_add_u64 v[36:37], s[6:7], 0, v[36:37]
	s_lshl_b32 s68, s18, 2
	v_lshl_add_u64 v[36:37], v[36:37], 0, s[68:69]
	s_mov_b32 s16, 0x4c0000
	v_add_co_u32_e32 v36, vcc, s16, v36
	s_load_dwordx2 s[16:17], s[12:13], 0x60
	s_or_b32 s18, s36, s18
	s_ashr_i32 s19, s18, 31
	s_lshl_b64 s[18:19], s[18:19], 2
	v_addc_co_u32_e32 v37, vcc, 0, v37, vcc
	s_waitcnt lgkmcnt(0)
	s_add_u32 s16, s16, s18
	s_addc_u32 s17, s17, s19
	global_load_dwordx2 v[42:43], v3, s[16:17]
	v_lshl_add_u64 v[4:5], v[12:13], 0, v[2:3]
	global_load_dwordx2 v[36:37], v[36:37], off
	v_lshl_add_u64 v[12:13], v[12:13], 0, v[76:77]
	v_lshl_add_u64 v[16:17], v[28:29], 0, v[2:3]
	v_lshl_add_u64 v[24:25], v[32:33], 0, v[2:3]
	v_lshl_add_u64 v[28:29], v[28:29], 0, v[76:77]
	v_lshl_add_u64 v[32:33], v[32:33], 0, v[76:77]
	global_load_dwordx4 v[4:7], v[4:5], off
	v_cmp_ne_u32_e32 vcc, 0, v204
	global_load_dwordx4 v[8:11], v[8:9], off
	global_load_dwordx4 v[12:15], v[12:13], off offset:2048
	global_load_dwordx4 v[16:19], v[16:17], off
	global_load_dwordx4 v[24:27], v[24:25], off
	global_load_dwordx4 v[28:31], v[28:29], off offset:2048
	global_load_dwordx4 v[32:35], v[32:33], off offset:2048
	s_waitcnt vmcnt(8)
	v_mul_f32_e32 v41, 0x3fb8aa3b, v42
	v_mul_f32_e32 v43, 0x3fb8aa3b, v43
	v_exp_f32_e32 v41, v41
	v_exp_f32_e32 v43, v43
	v_subbrev_co_u32_e64 v45, s[38:39], 0, v204, vcc
	s_waitcnt vmcnt(7)
	v_mul_f32_e64 v42, v36, -v41
	v_mul_f32_e64 v44, v37, -v43
	v_lshlrev_b32_e32 v45, 2, v45
	ds_bpermute_b32 v46, v45, v42
	ds_bpermute_b32 v45, v45, v44
	s_waitcnt lgkmcnt(1)
	v_fma_f32 v41, v36, -v41, v46
	s_waitcnt lgkmcnt(0)
	v_fma_f32 v43, v37, -v43, v45
	v_cndmask_b32_e32 v43, v44, v43, vcc
	v_cndmask_b32_e32 v41, v42, v41, vcc
	v_cmp_gt_u32_e32 vcc, 2, v204
	s_nop 1
	v_cndmask_b32_e64 v42, v226, 0, vcc
	v_add_lshl_u32 v42, v42, v204, 2
	ds_bpermute_b32 v44, v42, v41
	ds_bpermute_b32 v42, v42, v43
	s_waitcnt lgkmcnt(1)
	v_add_f32_e32 v44, v41, v44
	s_waitcnt lgkmcnt(0)
	v_add_f32_e32 v42, v43, v42
	v_cndmask_b32_e32 v42, v42, v43, vcc
	v_cndmask_b32_e32 v41, v44, v41, vcc
	v_cmp_gt_u32_e32 vcc, 4, v204
	s_nop 1
	v_cndmask_b32_e64 v43, v227, 0, vcc
	v_add_lshl_u32 v43, v43, v204, 2
	ds_bpermute_b32 v44, v43, v41
	ds_bpermute_b32 v43, v43, v42
	s_waitcnt lgkmcnt(1)
	v_add_f32_e32 v44, v41, v44
	s_waitcnt lgkmcnt(0)
	v_add_f32_e32 v43, v42, v43
	v_cndmask_b32_e32 v42, v43, v42, vcc
	v_cndmask_b32_e32 v41, v44, v41, vcc
	v_cmp_gt_u32_e32 vcc, 8, v204
	s_nop 1
	v_cndmask_b32_e64 v43, v228, 0, vcc
	v_add_lshl_u32 v43, v43, v204, 2
	ds_bpermute_b32 v44, v43, v41
	ds_bpermute_b32 v43, v43, v42
	s_waitcnt lgkmcnt(1)
	v_add_f32_e32 v44, v41, v44
	s_waitcnt lgkmcnt(0)
	v_add_f32_e32 v43, v42, v43
	v_cndmask_b32_e32 v42, v43, v42, vcc
	v_cndmask_b32_e32 v41, v44, v41, vcc
	v_cmp_gt_u32_e32 vcc, 16, v204
	s_nop 1
	v_cndmask_b32_e64 v43, v229, 0, vcc
	v_add_lshl_u32 v43, v43, v204, 2
	ds_bpermute_b32 v44, v43, v41
	ds_bpermute_b32 v43, v43, v42
	s_waitcnt lgkmcnt(1)
	v_add_f32_e32 v44, v41, v44
	s_waitcnt lgkmcnt(0)
	v_add_f32_e32 v43, v42, v43
	v_cndmask_b32_e32 v42, v43, v42, vcc
	v_cndmask_b32_e32 v43, v44, v41, vcc
	v_cmp_gt_u32_e32 vcc, 32, v204
	s_nop 1
	v_cndmask_b32_e64 v41, v230, 0, vcc
	v_add_lshl_u32 v41, v41, v204, 2
	ds_bpermute_b32 v44, v41, v43
	ds_bpermute_b32 v41, v41, v42
	s_waitcnt lgkmcnt(1)
	v_add_f32_e32 v44, v43, v44
	s_waitcnt lgkmcnt(0)
	v_add_f32_e32 v41, v42, v41
	v_cndmask_b32_e32 v41, v41, v42, vcc
	v_cndmask_b32_e32 v42, v44, v43, vcc
	v_readlane_b32 s19, v41, 63
	v_readlane_b32 s18, v42, 63
	v_cmp_eq_u32_e32 vcc, 0, v204
	s_and_saveexec_b64 s[16:17], vcc
	s_cbranch_execz .LBB0_418
	v_readlane_b32 s20, v254, 58
	s_lshl_b32 s20, s20, 2
	s_add_i32 s20, s20, 0
	s_add_i32 s20, s20, 0x14000
	v_mov_b32_e32 v43, s20
	v_mov_b32_e32 v44, s18
	v_mov_b32_e32 v45, s19
	ds_write2_b32 v43, v44, v45 offset1:8
